# P7 (MLP-out) epilogue rewritten by hand: accumulators permuted across lanes so a quad covers 64 contiguous bytes, coalesced residual loads/stores, DPP row sums, rolling loads
# speedup vs baseline: 1.0193x; 1.0030x over previous
.LBB0_1045:
	v_and_b32_e32 v197, 3, v194
	v_bfe_u32 v198, v194, 4, 2
	v_and_or_b32 v198, v194, 12, v198
	v_lshl_or_b32 v196, v197, 4, v198
	v_lshlrev_b32_e32 v196, 2, v196
	v_and_or_b32 v198, v188, -16, v198
	v_and_b32_e32 v199, 0x60, v190
	v_lshl_or_b32 v199, v197, 3, v199
	v_lshl_add_u32 v198, s68, 8, v198
	v_lshl_or_b32 v199, s69, 8, v199
	v_lshlrev_b32_e32 v176, 2, v198
	v_lshlrev_b32_e32 v198, 11, v198
	v_lshl_add_u32 v168, v199, 1, v198
	v_add_u32_e32 v169, 0x8000, v168
	v_add_u32_e32 v170, 0x10000, v168
	v_add_u32_e32 v171, 0x18000, v168
	v_add_u32_e32 v172, 0x40000, v168
	v_add_u32_e32 v173, 0x48000, v168
	v_add_u32_e32 v174, 0x50000, v168
	v_add_u32_e32 v175, 0x58000, v168
	s_mov_b32 s10, 0x11111111
	s_mov_b32 s11, s10
	global_load_dword v177, v176, s[14:15]
	global_load_dwordx4 v[128:131], v168, s[60:61]
	global_load_dwordx4 v[132:135], v168, s[60:61] offset:256
	global_load_dword v178, v176, s[14:15] offset:64
	global_load_dwordx4 v[136:139], v169, s[60:61]
	global_load_dwordx4 v[140:143], v169, s[60:61] offset:256
	global_load_dword v179, v176, s[14:15] offset:128
	global_load_dwordx4 v[144:147], v170, s[60:61]
	global_load_dwordx4 v[148:151], v170, s[60:61] offset:256
	global_load_dword v180, v176, s[14:15] offset:192
	global_load_dwordx4 v[204:207], v171, s[60:61]
	global_load_dwordx4 v[210:213], v171, s[60:61] offset:256
	ds_bpermute_b32 v124, v196, v124
	ds_bpermute_b32 v125, v196, v125
	ds_bpermute_b32 v126, v196, v126
	ds_bpermute_b32 v127, v196, v127
	ds_bpermute_b32 v120, v196, v120
	ds_bpermute_b32 v121, v196, v121
	ds_bpermute_b32 v122, v196, v122
	ds_bpermute_b32 v123, v196, v123
	ds_bpermute_b32 v108, v196, v108
	ds_bpermute_b32 v109, v196, v109
	ds_bpermute_b32 v110, v196, v110
	ds_bpermute_b32 v111, v196, v111
	ds_bpermute_b32 v104, v196, v104
	ds_bpermute_b32 v105, v196, v105
	ds_bpermute_b32 v106, v196, v106
	ds_bpermute_b32 v107, v196, v107
	ds_bpermute_b32 v92, v196, v92
	ds_bpermute_b32 v93, v196, v93
	ds_bpermute_b32 v94, v196, v94
	ds_bpermute_b32 v95, v196, v95
	ds_bpermute_b32 v88, v196, v88
	ds_bpermute_b32 v89, v196, v89
	ds_bpermute_b32 v90, v196, v90
	ds_bpermute_b32 v91, v196, v91
	ds_bpermute_b32 v76, v196, v76
	ds_bpermute_b32 v77, v196, v77
	ds_bpermute_b32 v78, v196, v78
	ds_bpermute_b32 v79, v196, v79
	ds_bpermute_b32 v72, v196, v72
	ds_bpermute_b32 v73, v196, v73
	ds_bpermute_b32 v74, v196, v74
	ds_bpermute_b32 v75, v196, v75
	s_and_b64 vcc, exec, s[38:39]
	s_cbranch_vccz .Lp7_nb
	s_barrier
.Lp7_nb:
	ds_bpermute_b32 v116, v196, v116
	ds_bpermute_b32 v117, v196, v117
	ds_bpermute_b32 v118, v196, v118
	ds_bpermute_b32 v119, v196, v119
	ds_bpermute_b32 v112, v196, v112
	ds_bpermute_b32 v113, v196, v113
	ds_bpermute_b32 v114, v196, v114
	ds_bpermute_b32 v115, v196, v115
	ds_bpermute_b32 v100, v196, v100
	ds_bpermute_b32 v101, v196, v101
	ds_bpermute_b32 v102, v196, v102
	ds_bpermute_b32 v103, v196, v103
	ds_bpermute_b32 v96, v196, v96
	ds_bpermute_b32 v97, v196, v97
	ds_bpermute_b32 v98, v196, v98
	ds_bpermute_b32 v99, v196, v99
	ds_bpermute_b32 v84, v196, v84
	ds_bpermute_b32 v85, v196, v85
	ds_bpermute_b32 v86, v196, v86
	ds_bpermute_b32 v87, v196, v87
	ds_bpermute_b32 v80, v196, v80
	ds_bpermute_b32 v81, v196, v81
	ds_bpermute_b32 v82, v196, v82
	ds_bpermute_b32 v83, v196, v83
	ds_bpermute_b32 v68, v196, v68
	ds_bpermute_b32 v69, v196, v69
	ds_bpermute_b32 v70, v196, v70
	ds_bpermute_b32 v71, v196, v71
	ds_bpermute_b32 v64, v196, v64
	ds_bpermute_b32 v65, v196, v65
	ds_bpermute_b32 v66, v196, v66
	ds_bpermute_b32 v67, v196, v67
	ds_bpermute_b32 v60, v196, v60
	ds_bpermute_b32 v61, v196, v61
	ds_bpermute_b32 v62, v196, v62
	ds_bpermute_b32 v63, v196, v63
	ds_bpermute_b32 v56, v196, v56
	ds_bpermute_b32 v57, v196, v57
	ds_bpermute_b32 v58, v196, v58
	ds_bpermute_b32 v59, v196, v59
	ds_bpermute_b32 v44, v196, v44
	ds_bpermute_b32 v45, v196, v45
	ds_bpermute_b32 v46, v196, v46
	ds_bpermute_b32 v47, v196, v47
	ds_bpermute_b32 v40, v196, v40
	ds_bpermute_b32 v41, v196, v41
	ds_bpermute_b32 v42, v196, v42
	ds_bpermute_b32 v43, v196, v43
	ds_bpermute_b32 v28, v196, v28
	ds_bpermute_b32 v29, v196, v29
	ds_bpermute_b32 v30, v196, v30
	ds_bpermute_b32 v31, v196, v31
	ds_bpermute_b32 v24, v196, v24
	ds_bpermute_b32 v25, v196, v25
	ds_bpermute_b32 v26, v196, v26
	ds_bpermute_b32 v27, v196, v27
	ds_bpermute_b32 v12, v196, v12
	ds_bpermute_b32 v13, v196, v13
	ds_bpermute_b32 v14, v196, v14
	ds_bpermute_b32 v15, v196, v15
	ds_bpermute_b32 v8, v196, v8
	ds_bpermute_b32 v9, v196, v9
	ds_bpermute_b32 v10, v196, v10
	ds_bpermute_b32 v11, v196, v11
	ds_bpermute_b32 v52, v196, v52
	ds_bpermute_b32 v53, v196, v53
	ds_bpermute_b32 v54, v196, v54
	ds_bpermute_b32 v55, v196, v55
	ds_bpermute_b32 v48, v196, v48
	ds_bpermute_b32 v49, v196, v49
	ds_bpermute_b32 v50, v196, v50
	ds_bpermute_b32 v51, v196, v51
	ds_bpermute_b32 v36, v196, v36
	ds_bpermute_b32 v37, v196, v37
	ds_bpermute_b32 v38, v196, v38
	ds_bpermute_b32 v39, v196, v39
	ds_bpermute_b32 v32, v196, v32
	ds_bpermute_b32 v33, v196, v33
	ds_bpermute_b32 v34, v196, v34
	ds_bpermute_b32 v35, v196, v35
	ds_bpermute_b32 v20, v196, v20
	ds_bpermute_b32 v21, v196, v21
	ds_bpermute_b32 v22, v196, v22
	ds_bpermute_b32 v23, v196, v23
	ds_bpermute_b32 v16, v196, v16
	ds_bpermute_b32 v17, v196, v17
	ds_bpermute_b32 v18, v196, v18
	ds_bpermute_b32 v19, v196, v19
	ds_bpermute_b32 v4, v196, v4
	ds_bpermute_b32 v5, v196, v5
	ds_bpermute_b32 v6, v196, v6
	ds_bpermute_b32 v7, v196, v7
	ds_bpermute_b32 v0, v196, v0
	ds_bpermute_b32 v1, v196, v1
	ds_bpermute_b32 v2, v196, v2
	ds_bpermute_b32 v3, v196, v3
	s_waitcnt lgkmcnt(0)
	s_waitcnt vmcnt(9)
	v_fmamk_f32 v202, v177, 0x3a800000, v195
	v_rcp_f32_e32 v202, v202
	v_lshlrev_b32_e32 v214, 16, v128
	v_and_b32_e32 v215, 0xffff0000, v128
	v_lshlrev_b32_e32 v216, 16, v129
	v_and_b32_e32 v217, 0xffff0000, v129
	v_lshlrev_b32_e32 v218, 16, v130
	v_and_b32_e32 v219, 0xffff0000, v130
	v_lshlrev_b32_e32 v220, 16, v131
	v_and_b32_e32 v221, 0xffff0000, v131
	v_pk_fma_f32 v[124:125], v[124:125], v[202:203], v[214:215] op_sel_hi:[1,0,1]
	v_pk_fma_f32 v[126:127], v[126:127], v[202:203], v[216:217] op_sel_hi:[1,0,1]
	v_pk_fma_f32 v[120:121], v[120:121], v[202:203], v[218:219] op_sel_hi:[1,0,1]
	v_pk_fma_f32 v[122:123], v[122:123], v[202:203], v[220:221] op_sel_hi:[1,0,1]
	v_mul_f32_e32 v181, v124, v124
	v_fmac_f32_e32 v181, v125, v125
	v_fmac_f32_e32 v181, v126, v126
	v_fmac_f32_e32 v181, v127, v127
	v_fmac_f32_e32 v181, v120, v120
	v_fmac_f32_e32 v181, v121, v121
	v_fmac_f32_e32 v181, v122, v122
	v_fmac_f32_e32 v181, v123, v123
	v_cvt_pk_bf16_f32 v124, v124, v125
	v_cvt_pk_bf16_f32 v125, v126, v127
	v_cvt_pk_bf16_f32 v126, v120, v121
	v_cvt_pk_bf16_f32 v127, v122, v123
	global_store_dwordx4 v168, v[124:127], s[28:29]
	v_lshlrev_b32_e32 v214, 16, v132
	v_and_b32_e32 v215, 0xffff0000, v132
	v_lshlrev_b32_e32 v216, 16, v133
	v_and_b32_e32 v217, 0xffff0000, v133
	v_lshlrev_b32_e32 v218, 16, v134
	v_and_b32_e32 v219, 0xffff0000, v134
	v_lshlrev_b32_e32 v220, 16, v135
	v_and_b32_e32 v221, 0xffff0000, v135
	v_pk_fma_f32 v[116:117], v[116:117], v[202:203], v[214:215] op_sel_hi:[1,0,1]
	v_pk_fma_f32 v[118:119], v[118:119], v[202:203], v[216:217] op_sel_hi:[1,0,1]
	v_pk_fma_f32 v[112:113], v[112:113], v[202:203], v[218:219] op_sel_hi:[1,0,1]
	v_pk_fma_f32 v[114:115], v[114:115], v[202:203], v[220:221] op_sel_hi:[1,0,1]
	v_fmac_f32_e32 v181, v116, v116
	v_fmac_f32_e32 v181, v117, v117
	v_fmac_f32_e32 v181, v118, v118
	v_fmac_f32_e32 v181, v119, v119
	v_fmac_f32_e32 v181, v112, v112
	v_fmac_f32_e32 v181, v113, v113
	v_fmac_f32_e32 v181, v114, v114
	v_fmac_f32_e32 v181, v115, v115
	v_cvt_pk_bf16_f32 v116, v116, v117
	v_cvt_pk_bf16_f32 v117, v118, v119
	v_cvt_pk_bf16_f32 v118, v112, v113
	v_cvt_pk_bf16_f32 v119, v114, v115
	global_store_dwordx4 v168, v[116:119], s[28:29] offset:256
	v_add_f32_dpp v181, v181, v181 quad_perm:[1,0,3,2] row_mask:0xf bank_mask:0xf
	s_nop 1
	v_add_f32_dpp v181, v181, v181 quad_perm:[2,3,0,1] row_mask:0xf bank_mask:0xf
	s_mov_b64 exec, s[10:11]
	global_atomic_add_f32 v176, v181, s[24:25]
	s_mov_b64 exec, -1
	global_load_dword v177, v176, s[14:15] offset:512
	global_load_dwordx4 v[128:131], v172, s[60:61]
	global_load_dwordx4 v[132:135], v172, s[60:61] offset:256
	s_waitcnt vmcnt(12)
	v_fmamk_f32 v202, v178, 0x3a800000, v195
	v_rcp_f32_e32 v202, v202
	v_lshlrev_b32_e32 v214, 16, v136
	v_and_b32_e32 v215, 0xffff0000, v136
	v_lshlrev_b32_e32 v216, 16, v137
	v_and_b32_e32 v217, 0xffff0000, v137
	v_lshlrev_b32_e32 v218, 16, v138
	v_and_b32_e32 v219, 0xffff0000, v138
	v_lshlrev_b32_e32 v220, 16, v139
	v_and_b32_e32 v221, 0xffff0000, v139
	v_pk_fma_f32 v[108:109], v[108:109], v[202:203], v[214:215] op_sel_hi:[1,0,1]
	v_pk_fma_f32 v[110:111], v[110:111], v[202:203], v[216:217] op_sel_hi:[1,0,1]
	v_pk_fma_f32 v[104:105], v[104:105], v[202:203], v[218:219] op_sel_hi:[1,0,1]
	v_pk_fma_f32 v[106:107], v[106:107], v[202:203], v[220:221] op_sel_hi:[1,0,1]
	v_mul_f32_e32 v182, v108, v108
	v_fmac_f32_e32 v182, v109, v109
	v_fmac_f32_e32 v182, v110, v110
	v_fmac_f32_e32 v182, v111, v111
	v_fmac_f32_e32 v182, v104, v104
	v_fmac_f32_e32 v182, v105, v105
	v_fmac_f32_e32 v182, v106, v106
	v_fmac_f32_e32 v182, v107, v107
	v_cvt_pk_bf16_f32 v108, v108, v109
	v_cvt_pk_bf16_f32 v109, v110, v111
	v_cvt_pk_bf16_f32 v110, v104, v105
	v_cvt_pk_bf16_f32 v111, v106, v107
	global_store_dwordx4 v169, v[108:111], s[28:29]
	v_lshlrev_b32_e32 v214, 16, v140
	v_and_b32_e32 v215, 0xffff0000, v140
	v_lshlrev_b32_e32 v216, 16, v141
	v_and_b32_e32 v217, 0xffff0000, v141
	v_lshlrev_b32_e32 v218, 16, v142
	v_and_b32_e32 v219, 0xffff0000, v142
	v_lshlrev_b32_e32 v220, 16, v143
	v_and_b32_e32 v221, 0xffff0000, v143
	v_pk_fma_f32 v[100:101], v[100:101], v[202:203], v[214:215] op_sel_hi:[1,0,1]
	v_pk_fma_f32 v[102:103], v[102:103], v[202:203], v[216:217] op_sel_hi:[1,0,1]
	v_pk_fma_f32 v[96:97], v[96:97], v[202:203], v[218:219] op_sel_hi:[1,0,1]
	v_pk_fma_f32 v[98:99], v[98:99], v[202:203], v[220:221] op_sel_hi:[1,0,1]
	v_fmac_f32_e32 v182, v100, v100
	v_fmac_f32_e32 v182, v101, v101
	v_fmac_f32_e32 v182, v102, v102
	v_fmac_f32_e32 v182, v103, v103
	v_fmac_f32_e32 v182, v96, v96
	v_fmac_f32_e32 v182, v97, v97
	v_fmac_f32_e32 v182, v98, v98
	v_fmac_f32_e32 v182, v99, v99
	v_cvt_pk_bf16_f32 v100, v100, v101
	v_cvt_pk_bf16_f32 v101, v102, v103
	v_cvt_pk_bf16_f32 v102, v96, v97
	v_cvt_pk_bf16_f32 v103, v98, v99
	global_store_dwordx4 v169, v[100:103], s[28:29] offset:256
	v_add_f32_dpp v182, v182, v182 quad_perm:[1,0,3,2] row_mask:0xf bank_mask:0xf
	s_nop 1
	v_add_f32_dpp v182, v182, v182 quad_perm:[2,3,0,1] row_mask:0xf bank_mask:0xf
	s_mov_b64 exec, s[10:11]
	global_atomic_add_f32 v176, v182, s[24:25] offset:64
	s_mov_b64 exec, -1
	global_load_dword v178, v176, s[14:15] offset:576
	global_load_dwordx4 v[136:139], v173, s[60:61]
	global_load_dwordx4 v[140:143], v173, s[60:61] offset:256
	s_waitcnt vmcnt(15)
	v_fmamk_f32 v202, v179, 0x3a800000, v195
	v_rcp_f32_e32 v202, v202
	v_lshlrev_b32_e32 v214, 16, v144
	v_and_b32_e32 v215, 0xffff0000, v144
	v_lshlrev_b32_e32 v216, 16, v145
	v_and_b32_e32 v217, 0xffff0000, v145
	v_lshlrev_b32_e32 v218, 16, v146
	v_and_b32_e32 v219, 0xffff0000, v146
	v_lshlrev_b32_e32 v220, 16, v147
	v_and_b32_e32 v221, 0xffff0000, v147
	v_pk_fma_f32 v[92:93], v[92:93], v[202:203], v[214:215] op_sel_hi:[1,0,1]
	v_pk_fma_f32 v[94:95], v[94:95], v[202:203], v[216:217] op_sel_hi:[1,0,1]
	v_pk_fma_f32 v[88:89], v[88:89], v[202:203], v[218:219] op_sel_hi:[1,0,1]
	v_pk_fma_f32 v[90:91], v[90:91], v[202:203], v[220:221] op_sel_hi:[1,0,1]
	v_mul_f32_e32 v181, v92, v92
	v_fmac_f32_e32 v181, v93, v93
	v_fmac_f32_e32 v181, v94, v94
	v_fmac_f32_e32 v181, v95, v95
	v_fmac_f32_e32 v181, v88, v88
	v_fmac_f32_e32 v181, v89, v89
	v_fmac_f32_e32 v181, v90, v90
	v_fmac_f32_e32 v181, v91, v91
	v_cvt_pk_bf16_f32 v92, v92, v93
	v_cvt_pk_bf16_f32 v93, v94, v95
	v_cvt_pk_bf16_f32 v94, v88, v89
	v_cvt_pk_bf16_f32 v95, v90, v91
	global_store_dwordx4 v170, v[92:95], s[28:29]
	v_lshlrev_b32_e32 v214, 16, v148
	v_and_b32_e32 v215, 0xffff0000, v148
	v_lshlrev_b32_e32 v216, 16, v149
	v_and_b32_e32 v217, 0xffff0000, v149
	v_lshlrev_b32_e32 v218, 16, v150
	v_and_b32_e32 v219, 0xffff0000, v150
	v_lshlrev_b32_e32 v220, 16, v151
	v_and_b32_e32 v221, 0xffff0000, v151
	v_pk_fma_f32 v[84:85], v[84:85], v[202:203], v[214:215] op_sel_hi:[1,0,1]
	v_pk_fma_f32 v[86:87], v[86:87], v[202:203], v[216:217] op_sel_hi:[1,0,1]
	v_pk_fma_f32 v[80:81], v[80:81], v[202:203], v[218:219] op_sel_hi:[1,0,1]
	v_pk_fma_f32 v[82:83], v[82:83], v[202:203], v[220:221] op_sel_hi:[1,0,1]
	v_fmac_f32_e32 v181, v84, v84
	v_fmac_f32_e32 v181, v85, v85
	v_fmac_f32_e32 v181, v86, v86
	v_fmac_f32_e32 v181, v87, v87
	v_fmac_f32_e32 v181, v80, v80
	v_fmac_f32_e32 v181, v81, v81
	v_fmac_f32_e32 v181, v82, v82
	v_fmac_f32_e32 v181, v83, v83
	v_cvt_pk_bf16_f32 v84, v84, v85
	v_cvt_pk_bf16_f32 v85, v86, v87
	v_cvt_pk_bf16_f32 v86, v80, v81
	v_cvt_pk_bf16_f32 v87, v82, v83
	global_store_dwordx4 v170, v[84:87], s[28:29] offset:256
	v_add_f32_dpp v181, v181, v181 quad_perm:[1,0,3,2] row_mask:0xf bank_mask:0xf
	s_nop 1
	v_add_f32_dpp v181, v181, v181 quad_perm:[2,3,0,1] row_mask:0xf bank_mask:0xf
	s_mov_b64 exec, s[10:11]
	global_atomic_add_f32 v176, v181, s[24:25] offset:128
	s_mov_b64 exec, -1
	global_load_dword v179, v176, s[14:15] offset:640
	global_load_dwordx4 v[144:147], v174, s[60:61]
	global_load_dwordx4 v[148:151], v174, s[60:61] offset:256
	s_waitcnt vmcnt(18)
	v_fmamk_f32 v202, v180, 0x3a800000, v195
	v_rcp_f32_e32 v202, v202
	v_lshlrev_b32_e32 v214, 16, v204
	v_and_b32_e32 v215, 0xffff0000, v204
	v_lshlrev_b32_e32 v216, 16, v205
	v_and_b32_e32 v217, 0xffff0000, v205
	v_lshlrev_b32_e32 v218, 16, v206
	v_and_b32_e32 v219, 0xffff0000, v206
	v_lshlrev_b32_e32 v220, 16, v207
	v_and_b32_e32 v221, 0xffff0000, v207
	v_pk_fma_f32 v[76:77], v[76:77], v[202:203], v[214:215] op_sel_hi:[1,0,1]
	v_pk_fma_f32 v[78:79], v[78:79], v[202:203], v[216:217] op_sel_hi:[1,0,1]
	v_pk_fma_f32 v[72:73], v[72:73], v[202:203], v[218:219] op_sel_hi:[1,0,1]
	v_pk_fma_f32 v[74:75], v[74:75], v[202:203], v[220:221] op_sel_hi:[1,0,1]
	v_mul_f32_e32 v182, v76, v76
	v_fmac_f32_e32 v182, v77, v77
	v_fmac_f32_e32 v182, v78, v78
	v_fmac_f32_e32 v182, v79, v79
	v_fmac_f32_e32 v182, v72, v72
	v_fmac_f32_e32 v182, v73, v73
	v_fmac_f32_e32 v182, v74, v74
	v_fmac_f32_e32 v182, v75, v75
	v_cvt_pk_bf16_f32 v76, v76, v77
	v_cvt_pk_bf16_f32 v77, v78, v79
	v_cvt_pk_bf16_f32 v78, v72, v73
	v_cvt_pk_bf16_f32 v79, v74, v75
	global_store_dwordx4 v171, v[76:79], s[28:29]
	v_lshlrev_b32_e32 v214, 16, v210
	v_and_b32_e32 v215, 0xffff0000, v210
	v_lshlrev_b32_e32 v216, 16, v211
	v_and_b32_e32 v217, 0xffff0000, v211
	v_lshlrev_b32_e32 v218, 16, v212
	v_and_b32_e32 v219, 0xffff0000, v212
	v_lshlrev_b32_e32 v220, 16, v213
	v_and_b32_e32 v221, 0xffff0000, v213
	v_pk_fma_f32 v[68:69], v[68:69], v[202:203], v[214:215] op_sel_hi:[1,0,1]
	v_pk_fma_f32 v[70:71], v[70:71], v[202:203], v[216:217] op_sel_hi:[1,0,1]
	v_pk_fma_f32 v[64:65], v[64:65], v[202:203], v[218:219] op_sel_hi:[1,0,1]
	v_pk_fma_f32 v[66:67], v[66:67], v[202:203], v[220:221] op_sel_hi:[1,0,1]
	v_fmac_f32_e32 v182, v68, v68
	v_fmac_f32_e32 v182, v69, v69
	v_fmac_f32_e32 v182, v70, v70
	v_fmac_f32_e32 v182, v71, v71
	v_fmac_f32_e32 v182, v64, v64
	v_fmac_f32_e32 v182, v65, v65
	v_fmac_f32_e32 v182, v66, v66
	v_fmac_f32_e32 v182, v67, v67
	v_cvt_pk_bf16_f32 v68, v68, v69
	v_cvt_pk_bf16_f32 v69, v70, v71
	v_cvt_pk_bf16_f32 v70, v64, v65
	v_cvt_pk_bf16_f32 v71, v66, v67
	global_store_dwordx4 v171, v[68:71], s[28:29] offset:256
	v_add_f32_dpp v182, v182, v182 quad_perm:[1,0,3,2] row_mask:0xf bank_mask:0xf
	s_nop 1
	v_add_f32_dpp v182, v182, v182 quad_perm:[2,3,0,1] row_mask:0xf bank_mask:0xf
	s_mov_b64 exec, s[10:11]
	global_atomic_add_f32 v176, v182, s[24:25] offset:192
	s_mov_b64 exec, -1
	global_load_dword v180, v176, s[14:15] offset:704
	global_load_dwordx4 v[204:207], v175, s[60:61]
	global_load_dwordx4 v[210:213], v175, s[60:61] offset:256
	s_waitcnt vmcnt(18)
	v_fmamk_f32 v202, v177, 0x3a800000, v195
	v_rcp_f32_e32 v202, v202
	v_lshlrev_b32_e32 v214, 16, v128
	v_and_b32_e32 v215, 0xffff0000, v128
	v_lshlrev_b32_e32 v216, 16, v129
	v_and_b32_e32 v217, 0xffff0000, v129
	v_lshlrev_b32_e32 v218, 16, v130
	v_and_b32_e32 v219, 0xffff0000, v130
	v_lshlrev_b32_e32 v220, 16, v131
	v_and_b32_e32 v221, 0xffff0000, v131
	v_pk_fma_f32 v[60:61], v[60:61], v[202:203], v[214:215] op_sel_hi:[1,0,1]
	v_pk_fma_f32 v[62:63], v[62:63], v[202:203], v[216:217] op_sel_hi:[1,0,1]
	v_pk_fma_f32 v[56:57], v[56:57], v[202:203], v[218:219] op_sel_hi:[1,0,1]
	v_pk_fma_f32 v[58:59], v[58:59], v[202:203], v[220:221] op_sel_hi:[1,0,1]
	v_mul_f32_e32 v181, v60, v60
	v_fmac_f32_e32 v181, v61, v61
	v_fmac_f32_e32 v181, v62, v62
	v_fmac_f32_e32 v181, v63, v63
	v_fmac_f32_e32 v181, v56, v56
	v_fmac_f32_e32 v181, v57, v57
	v_fmac_f32_e32 v181, v58, v58
	v_fmac_f32_e32 v181, v59, v59
	v_cvt_pk_bf16_f32 v60, v60, v61
	v_cvt_pk_bf16_f32 v61, v62, v63
	v_cvt_pk_bf16_f32 v62, v56, v57
	v_cvt_pk_bf16_f32 v63, v58, v59
	global_store_dwordx4 v172, v[60:63], s[28:29]
	v_lshlrev_b32_e32 v214, 16, v132
	v_and_b32_e32 v215, 0xffff0000, v132
	v_lshlrev_b32_e32 v216, 16, v133
	v_and_b32_e32 v217, 0xffff0000, v133
	v_lshlrev_b32_e32 v218, 16, v134
	v_and_b32_e32 v219, 0xffff0000, v134
	v_lshlrev_b32_e32 v220, 16, v135
	v_and_b32_e32 v221, 0xffff0000, v135
	v_pk_fma_f32 v[52:53], v[52:53], v[202:203], v[214:215] op_sel_hi:[1,0,1]
	v_pk_fma_f32 v[54:55], v[54:55], v[202:203], v[216:217] op_sel_hi:[1,0,1]
	v_pk_fma_f32 v[48:49], v[48:49], v[202:203], v[218:219] op_sel_hi:[1,0,1]
	v_pk_fma_f32 v[50:51], v[50:51], v[202:203], v[220:221] op_sel_hi:[1,0,1]
	v_fmac_f32_e32 v181, v52, v52
	v_fmac_f32_e32 v181, v53, v53
	v_fmac_f32_e32 v181, v54, v54
	v_fmac_f32_e32 v181, v55, v55
	v_fmac_f32_e32 v181, v48, v48
	v_fmac_f32_e32 v181, v49, v49
	v_fmac_f32_e32 v181, v50, v50
	v_fmac_f32_e32 v181, v51, v51
	v_cvt_pk_bf16_f32 v52, v52, v53
	v_cvt_pk_bf16_f32 v53, v54, v55
	v_cvt_pk_bf16_f32 v54, v48, v49
	v_cvt_pk_bf16_f32 v55, v50, v51
	global_store_dwordx4 v172, v[52:55], s[28:29] offset:256
	v_add_f32_dpp v181, v181, v181 quad_perm:[1,0,3,2] row_mask:0xf bank_mask:0xf
	s_nop 1
	v_add_f32_dpp v181, v181, v181 quad_perm:[2,3,0,1] row_mask:0xf bank_mask:0xf
	s_mov_b64 exec, s[10:11]
	global_atomic_add_f32 v176, v181, s[24:25] offset:512
	s_mov_b64 exec, -1
	s_waitcnt vmcnt(15)
	v_fmamk_f32 v202, v178, 0x3a800000, v195
	v_rcp_f32_e32 v202, v202
	v_lshlrev_b32_e32 v214, 16, v136
	v_and_b32_e32 v215, 0xffff0000, v136
	v_lshlrev_b32_e32 v216, 16, v137
	v_and_b32_e32 v217, 0xffff0000, v137
	v_lshlrev_b32_e32 v218, 16, v138
	v_and_b32_e32 v219, 0xffff0000, v138
	v_lshlrev_b32_e32 v220, 16, v139
	v_and_b32_e32 v221, 0xffff0000, v139
	v_pk_fma_f32 v[44:45], v[44:45], v[202:203], v[214:215] op_sel_hi:[1,0,1]
	v_pk_fma_f32 v[46:47], v[46:47], v[202:203], v[216:217] op_sel_hi:[1,0,1]
	v_pk_fma_f32 v[40:41], v[40:41], v[202:203], v[218:219] op_sel_hi:[1,0,1]
	v_pk_fma_f32 v[42:43], v[42:43], v[202:203], v[220:221] op_sel_hi:[1,0,1]
	v_mul_f32_e32 v182, v44, v44
	v_fmac_f32_e32 v182, v45, v45
	v_fmac_f32_e32 v182, v46, v46
	v_fmac_f32_e32 v182, v47, v47
	v_fmac_f32_e32 v182, v40, v40
	v_fmac_f32_e32 v182, v41, v41
	v_fmac_f32_e32 v182, v42, v42
	v_fmac_f32_e32 v182, v43, v43
	v_cvt_pk_bf16_f32 v44, v44, v45
	v_cvt_pk_bf16_f32 v45, v46, v47
	v_cvt_pk_bf16_f32 v46, v40, v41
	v_cvt_pk_bf16_f32 v47, v42, v43
	global_store_dwordx4 v173, v[44:47], s[28:29]
	v_lshlrev_b32_e32 v214, 16, v140
	v_and_b32_e32 v215, 0xffff0000, v140
	v_lshlrev_b32_e32 v216, 16, v141
	v_and_b32_e32 v217, 0xffff0000, v141
	v_lshlrev_b32_e32 v218, 16, v142
	v_and_b32_e32 v219, 0xffff0000, v142
	v_lshlrev_b32_e32 v220, 16, v143
	v_and_b32_e32 v221, 0xffff0000, v143
	v_pk_fma_f32 v[36:37], v[36:37], v[202:203], v[214:215] op_sel_hi:[1,0,1]
	v_pk_fma_f32 v[38:39], v[38:39], v[202:203], v[216:217] op_sel_hi:[1,0,1]
	v_pk_fma_f32 v[32:33], v[32:33], v[202:203], v[218:219] op_sel_hi:[1,0,1]
	v_pk_fma_f32 v[34:35], v[34:35], v[202:203], v[220:221] op_sel_hi:[1,0,1]
	v_fmac_f32_e32 v182, v36, v36
	v_fmac_f32_e32 v182, v37, v37
	v_fmac_f32_e32 v182, v38, v38
	v_fmac_f32_e32 v182, v39, v39
	v_fmac_f32_e32 v182, v32, v32
	v_fmac_f32_e32 v182, v33, v33
	v_fmac_f32_e32 v182, v34, v34
	v_fmac_f32_e32 v182, v35, v35
	v_cvt_pk_bf16_f32 v36, v36, v37
	v_cvt_pk_bf16_f32 v37, v38, v39
	v_cvt_pk_bf16_f32 v38, v32, v33
	v_cvt_pk_bf16_f32 v39, v34, v35
	global_store_dwordx4 v173, v[36:39], s[28:29] offset:256
	v_add_f32_dpp v182, v182, v182 quad_perm:[1,0,3,2] row_mask:0xf bank_mask:0xf
	s_nop 1
	v_add_f32_dpp v182, v182, v182 quad_perm:[2,3,0,1] row_mask:0xf bank_mask:0xf
	s_mov_b64 exec, s[10:11]
	global_atomic_add_f32 v176, v182, s[24:25] offset:576
	s_mov_b64 exec, -1
	s_waitcnt vmcnt(12)
	v_fmamk_f32 v202, v179, 0x3a800000, v195
	v_rcp_f32_e32 v202, v202
	v_lshlrev_b32_e32 v214, 16, v144
	v_and_b32_e32 v215, 0xffff0000, v144
	v_lshlrev_b32_e32 v216, 16, v145
	v_and_b32_e32 v217, 0xffff0000, v145
	v_lshlrev_b32_e32 v218, 16, v146
	v_and_b32_e32 v219, 0xffff0000, v146
	v_lshlrev_b32_e32 v220, 16, v147
	v_and_b32_e32 v221, 0xffff0000, v147
	v_pk_fma_f32 v[28:29], v[28:29], v[202:203], v[214:215] op_sel_hi:[1,0,1]
	v_pk_fma_f32 v[30:31], v[30:31], v[202:203], v[216:217] op_sel_hi:[1,0,1]
	v_pk_fma_f32 v[24:25], v[24:25], v[202:203], v[218:219] op_sel_hi:[1,0,1]
	v_pk_fma_f32 v[26:27], v[26:27], v[202:203], v[220:221] op_sel_hi:[1,0,1]
	v_mul_f32_e32 v181, v28, v28
	v_fmac_f32_e32 v181, v29, v29
	v_fmac_f32_e32 v181, v30, v30
	v_fmac_f32_e32 v181, v31, v31
	v_fmac_f32_e32 v181, v24, v24
	v_fmac_f32_e32 v181, v25, v25
	v_fmac_f32_e32 v181, v26, v26
	v_fmac_f32_e32 v181, v27, v27
	v_cvt_pk_bf16_f32 v28, v28, v29
	v_cvt_pk_bf16_f32 v29, v30, v31
	v_cvt_pk_bf16_f32 v30, v24, v25
	v_cvt_pk_bf16_f32 v31, v26, v27
	global_store_dwordx4 v174, v[28:31], s[28:29]
	v_lshlrev_b32_e32 v214, 16, v148
	v_and_b32_e32 v215, 0xffff0000, v148
	v_lshlrev_b32_e32 v216, 16, v149
	v_and_b32_e32 v217, 0xffff0000, v149
	v_lshlrev_b32_e32 v218, 16, v150
	v_and_b32_e32 v219, 0xffff0000, v150
	v_lshlrev_b32_e32 v220, 16, v151
	v_and_b32_e32 v221, 0xffff0000, v151
	v_pk_fma_f32 v[20:21], v[20:21], v[202:203], v[214:215] op_sel_hi:[1,0,1]
	v_pk_fma_f32 v[22:23], v[22:23], v[202:203], v[216:217] op_sel_hi:[1,0,1]
	v_pk_fma_f32 v[16:17], v[16:17], v[202:203], v[218:219] op_sel_hi:[1,0,1]
	v_pk_fma_f32 v[18:19], v[18:19], v[202:203], v[220:221] op_sel_hi:[1,0,1]
	v_fmac_f32_e32 v181, v20, v20
	v_fmac_f32_e32 v181, v21, v21
	v_fmac_f32_e32 v181, v22, v22
	v_fmac_f32_e32 v181, v23, v23
	v_fmac_f32_e32 v181, v16, v16
	v_fmac_f32_e32 v181, v17, v17
	v_fmac_f32_e32 v181, v18, v18
	v_fmac_f32_e32 v181, v19, v19
	v_cvt_pk_bf16_f32 v20, v20, v21
	v_cvt_pk_bf16_f32 v21, v22, v23
	v_cvt_pk_bf16_f32 v22, v16, v17
	v_cvt_pk_bf16_f32 v23, v18, v19
	global_store_dwordx4 v174, v[20:23], s[28:29] offset:256
	v_add_f32_dpp v181, v181, v181 quad_perm:[1,0,3,2] row_mask:0xf bank_mask:0xf
	s_nop 1
	v_add_f32_dpp v181, v181, v181 quad_perm:[2,3,0,1] row_mask:0xf bank_mask:0xf
	s_mov_b64 exec, s[10:11]
	global_atomic_add_f32 v176, v181, s[24:25] offset:640
	s_mov_b64 exec, -1
	s_waitcnt vmcnt(9)
	v_fmamk_f32 v202, v180, 0x3a800000, v195
	v_rcp_f32_e32 v202, v202
	v_lshlrev_b32_e32 v214, 16, v204
	v_and_b32_e32 v215, 0xffff0000, v204
	v_lshlrev_b32_e32 v216, 16, v205
	v_and_b32_e32 v217, 0xffff0000, v205
	v_lshlrev_b32_e32 v218, 16, v206
	v_and_b32_e32 v219, 0xffff0000, v206
	v_lshlrev_b32_e32 v220, 16, v207
	v_and_b32_e32 v221, 0xffff0000, v207
	v_pk_fma_f32 v[12:13], v[12:13], v[202:203], v[214:215] op_sel_hi:[1,0,1]
	v_pk_fma_f32 v[14:15], v[14:15], v[202:203], v[216:217] op_sel_hi:[1,0,1]
	v_pk_fma_f32 v[8:9], v[8:9], v[202:203], v[218:219] op_sel_hi:[1,0,1]
	v_pk_fma_f32 v[10:11], v[10:11], v[202:203], v[220:221] op_sel_hi:[1,0,1]
	v_mul_f32_e32 v182, v12, v12
	v_fmac_f32_e32 v182, v13, v13
	v_fmac_f32_e32 v182, v14, v14
	v_fmac_f32_e32 v182, v15, v15
	v_fmac_f32_e32 v182, v8, v8
	v_fmac_f32_e32 v182, v9, v9
	v_fmac_f32_e32 v182, v10, v10
	v_fmac_f32_e32 v182, v11, v11
	v_cvt_pk_bf16_f32 v12, v12, v13
	v_cvt_pk_bf16_f32 v13, v14, v15
	v_cvt_pk_bf16_f32 v14, v8, v9
	v_cvt_pk_bf16_f32 v15, v10, v11
	global_store_dwordx4 v175, v[12:15], s[28:29]
	v_lshlrev_b32_e32 v214, 16, v210
	v_and_b32_e32 v215, 0xffff0000, v210
	v_lshlrev_b32_e32 v216, 16, v211
	v_and_b32_e32 v217, 0xffff0000, v211
	v_lshlrev_b32_e32 v218, 16, v212
	v_and_b32_e32 v219, 0xffff0000, v212
	v_lshlrev_b32_e32 v220, 16, v213
	v_and_b32_e32 v221, 0xffff0000, v213
	v_pk_fma_f32 v[4:5], v[4:5], v[202:203], v[214:215] op_sel_hi:[1,0,1]
	v_pk_fma_f32 v[6:7], v[6:7], v[202:203], v[216:217] op_sel_hi:[1,0,1]
	v_pk_fma_f32 v[0:1], v[0:1], v[202:203], v[218:219] op_sel_hi:[1,0,1]
	v_pk_fma_f32 v[2:3], v[2:3], v[202:203], v[220:221] op_sel_hi:[1,0,1]
	v_fmac_f32_e32 v182, v4, v4
	v_fmac_f32_e32 v182, v5, v5
	v_fmac_f32_e32 v182, v6, v6
	v_fmac_f32_e32 v182, v7, v7
	v_fmac_f32_e32 v182, v0, v0
	v_fmac_f32_e32 v182, v1, v1
	v_fmac_f32_e32 v182, v2, v2
	v_fmac_f32_e32 v182, v3, v3
	v_cvt_pk_bf16_f32 v4, v4, v5
	v_cvt_pk_bf16_f32 v5, v6, v7
	v_cvt_pk_bf16_f32 v6, v0, v1
	v_cvt_pk_bf16_f32 v7, v2, v3
	global_store_dwordx4 v175, v[4:7], s[28:29] offset:256
	v_add_f32_dpp v182, v182, v182 quad_perm:[1,0,3,2] row_mask:0xf bank_mask:0xf
	s_nop 1
	v_add_f32_dpp v182, v182, v182 quad_perm:[2,3,0,1] row_mask:0xf bank_mask:0xf
	s_mov_b64 exec, s[10:11]
	global_atomic_add_f32 v176, v182, s[24:25] offset:704
	s_mov_b64 exec, -1
	s_and_b64 vcc, exec, s[6:7]
	s_mov_b64 s[6:7], -1
	s_cbranch_vccnz .LBB0_1031
	s_andn2_b64 vcc, exec, s[22:23]
	s_cbranch_vccnz .LBB0_1030
	s_barrier
	s_branch .LBB0_1030
